# attention: thresholded lazy rescale (the output-accumulator rescale is skipped when no query's running max rose by more than 8 in the log2 domain; stale max kept as the reference, exact softmax algebr
# baseline (speedup 1.0000x reference)
.LBB0_275:
	s_nop 0
	v_and_b32_e32 v2, 64, v224
	v_xor_b32_e32 v198, 32, v224
	v_add_u32_e32 v230, 64, v2
	v_cmp_lt_i32_e32 vcc, v198, v230
	v_cndmask_b32_e64 v3, 0, 1, s[16:17]
	v_cmp_ne_u32_e64 s[36:37], 1, v3
	v_cndmask_b32_e32 v2, v224, v198, vcc
	v_lshlrev_b32_e32 v247, 2, v2
	v_mov_b32_e32 v2, v178
	v_mov_b32_e32 v3, v178
	s_andn2_b64 vcc, exec, s[16:17]
	s_mov_b64 s[16:17], -1
	s_waitcnt lgkmcnt(0)
	v_permlane32_swap_b32_e32 v2, v3
	v_max_f32_e32 v2, v2, v3
	v_max3_f32 v179, v221, v178, v2
	v_sub_f32_e32 v2, v179, v221
	v_mov_b32_e32 v3, 0x41000000
	v_cmp_lt_f32_e64 s[82:83], v3, v2
	s_cmp_lg_u64 s[82:83], 0
	s_cselect_b32 s73, 1, 0
	s_cbranch_scc1 .Lat_need0
	v_mov_b32_e32 v179, v221
.Lat_need0:
	s_cbranch_vccnz .LBB0_277
	v_sub_f32_e32 v2, v218, v179
	v_exp_f32_e32 v2, v2
	v_sub_f32_e32 v3, v219, v179
	v_exp_f32_e32 v3, v3
	v_sub_f32_e32 v4, v216, v179
	v_exp_f32_e32 v4, v4
	v_sub_f32_e32 v5, v217, v179
	v_exp_f32_e32 v5, v5
	v_add_f32_e32 v6, 0, v2
	v_add_f32_e32 v6, v3, v6
	v_add_f32_e32 v6, v4, v6
	v_add_f32_e32 v10, v5, v6
	v_sub_f32_e32 v6, v214, v179
	v_exp_f32_e32 v6, v6
	v_sub_f32_e32 v7, v215, v179
	v_exp_f32_e32 v7, v7
	v_sub_f32_e32 v8, v208, v179
	v_exp_f32_e32 v8, v8
	v_sub_f32_e32 v9, v209, v179
	v_exp_f32_e32 v9, v9
	v_add_f32_e32 v10, v6, v10
	v_add_f32_e32 v10, v7, v10
	v_add_f32_e32 v10, v8, v10
	v_add_f32_e32 v14, v9, v10
	v_sub_f32_e32 v10, v212, v179
	v_exp_f32_e32 v10, v10
	v_sub_f32_e32 v11, v213, v179
	v_exp_f32_e32 v11, v11
	v_sub_f32_e32 v12, v206, v179
	v_exp_f32_e32 v12, v12
	v_sub_f32_e32 v13, v207, v179
	v_exp_f32_e32 v13, v13
	v_add_f32_e32 v14, v10, v14
	v_add_f32_e32 v14, v11, v14
	v_add_f32_e32 v14, v12, v14
	v_add_f32_e32 v18, v13, v14
	v_sub_f32_e32 v14, v202, v179
	v_exp_f32_e32 v14, v14
	v_sub_f32_e32 v15, v203, v179
	v_exp_f32_e32 v15, v15
	v_sub_f32_e32 v16, v192, v179
	v_exp_f32_e32 v16, v16
	v_sub_f32_e32 v17, v193, v179
	v_exp_f32_e32 v17, v17
	v_add_f32_e32 v18, v14, v18
	v_add_f32_e32 v18, v15, v18
	v_add_f32_e32 v18, v16, v18
	v_add_f32_e32 v22, v17, v18
	v_sub_f32_e32 v18, v210, v179
	v_exp_f32_e32 v18, v18
	v_sub_f32_e32 v19, v211, v179
	v_exp_f32_e32 v19, v19
	v_sub_f32_e32 v20, v204, v179
	v_exp_f32_e32 v20, v20
	v_sub_f32_e32 v21, v205, v179
	v_exp_f32_e32 v21, v21
	v_add_f32_e32 v22, v18, v22
	v_add_f32_e32 v22, v19, v22
	v_add_f32_e32 v22, v20, v22
	v_add_f32_e32 v26, v21, v22
	v_sub_f32_e32 v22, v194, v179
	v_exp_f32_e32 v22, v22
	v_sub_f32_e32 v23, v195, v179
	v_exp_f32_e32 v23, v23
	v_sub_f32_e32 v24, v190, v179
	v_exp_f32_e32 v24, v24
	v_sub_f32_e32 v25, v191, v179
	v_exp_f32_e32 v25, v25
	v_add_f32_e32 v26, v22, v26
	v_add_f32_e32 v26, v23, v26
	v_add_f32_e32 v26, v24, v26
	v_add_f32_e32 v30, v25, v26
	v_sub_f32_e32 v26, v188, v179
	v_exp_f32_e32 v26, v26
	v_sub_f32_e32 v27, v189, v179
	v_exp_f32_e32 v27, v27
	v_sub_f32_e32 v28, v186, v179
	v_exp_f32_e32 v28, v28
	v_sub_f32_e32 v29, v187, v179
	v_exp_f32_e32 v29, v29
	v_add_f32_e32 v30, v26, v30
	v_add_f32_e32 v30, v27, v30
	v_add_f32_e32 v30, v28, v30
	v_add_f32_e32 v33, v29, v30
	v_sub_f32_e32 v30, v184, v179
	v_exp_f32_e32 v30, v30
	v_sub_f32_e32 v31, v185, v179
	v_exp_f32_e32 v31, v31
	v_sub_f32_e32 v32, v182, v179
	v_exp_f32_e32 v32, v32
	v_add_f32_e32 v33, v30, v33
	v_add_f32_e32 v178, v31, v33
	v_pk_add_f32 v[180:181], v[182:183], v[178:179] neg_lo:[0,1] neg_hi:[0,1]
	s_mov_b64 s[16:17], 0
	v_add_f32_e32 v180, v32, v178

.LBB0_279:
	v_sub_f32_e32 v33, v221, v179
	v_exp_f32_e32 v178, v33
	v_cvt_pk_bf16_f32 v2, v2, v3
	v_cvt_pk_bf16_f32 v3, v4, v5
	v_cvt_pk_bf16_f32 v4, v6, v7
	v_cvt_pk_bf16_f32 v5, v8, v9
	v_exp_f32_e32 v181, v181
	s_cmp_eq_u32 s73, 0
	s_cbranch_scc1 .Lat_skip0
	v_pk_mul_f32 v[96:97], v[96:97], v[178:179] op_sel_hi:[1,0]
	v_pk_mul_f32 v[94:95], v[94:95], v[178:179] op_sel_hi:[1,0]
	v_pk_mul_f32 v[92:93], v[92:93], v[178:179] op_sel_hi:[1,0]
	v_pk_mul_f32 v[90:91], v[90:91], v[178:179] op_sel_hi:[1,0]
	v_pk_mul_f32 v[88:89], v[88:89], v[178:179] op_sel_hi:[1,0]
	v_pk_mul_f32 v[86:87], v[86:87], v[178:179] op_sel_hi:[1,0]
	v_pk_mul_f32 v[84:85], v[84:85], v[178:179] op_sel_hi:[1,0]
	v_pk_mul_f32 v[82:83], v[82:83], v[178:179] op_sel_hi:[1,0]
	v_pk_mul_f32 v[80:81], v[80:81], v[178:179] op_sel_hi:[1,0]
	v_pk_mul_f32 v[78:79], v[78:79], v[178:179] op_sel_hi:[1,0]
	v_pk_mul_f32 v[76:77], v[76:77], v[178:179] op_sel_hi:[1,0]
	v_pk_mul_f32 v[74:75], v[74:75], v[178:179] op_sel_hi:[1,0]
	v_pk_mul_f32 v[72:73], v[72:73], v[178:179] op_sel_hi:[1,0]
	v_pk_mul_f32 v[70:71], v[70:71], v[178:179] op_sel_hi:[1,0]
	v_pk_mul_f32 v[68:69], v[68:69], v[178:179] op_sel_hi:[1,0]
	v_pk_mul_f32 v[66:67], v[66:67], v[178:179] op_sel_hi:[1,0]
.Lat_skip0:
	s_waitcnt vmcnt(0)
	v_mfma_f32_32x32x16_bf16 v[82:97], v[118:121], v[2:5], v[82:97]
	s_cmp_lg_u32 s33, 8
	s_cselect_b64 s[16:17], -1, 0
	v_lshlrev_b32_e32 v194, 3, v246
	s_cmp_eq_u32 s33, 8
	v_mfma_f32_32x32x16_bf16 v[66:81], v[110:113], v[2:5], v[66:81]
	v_cvt_pk_bf16_f32 v2, v10, v11
	v_cvt_pk_bf16_f32 v3, v12, v13
	v_cvt_pk_bf16_f32 v4, v14, v15
	v_cvt_pk_bf16_f32 v5, v16, v17
	s_nop 0
	v_mfma_f32_32x32x16_bf16 v[82:97], v[114:117], v[2:5], v[82:97]
	v_mfma_f32_32x32x16_bf16 v[66:81], v[106:109], v[2:5], v[66:81]
	v_cvt_pk_bf16_f32 v2, v18, v19
	v_cvt_pk_bf16_f32 v3, v20, v21
	v_cvt_pk_bf16_f32 v4, v22, v23
	v_cvt_pk_bf16_f32 v5, v24, v25
	s_nop 0
	v_mfma_f32_32x32x16_bf16 v[82:97], v[102:105], v[2:5], v[82:97]
	v_mfma_f32_32x32x16_bf16 v[66:81], v[142:145], v[2:5], v[66:81]
	v_cvt_pk_bf16_f32 v2, v26, v27
	v_cvt_pk_bf16_f32 v3, v28, v29
	v_cvt_pk_bf16_f32 v4, v30, v31
	v_cvt_pk_bf16_f32 v5, v32, v181
	s_nop 0
	v_mfma_f32_32x32x16_bf16 v[82:97], v[98:101], v[2:5], v[82:97]
	v_mfma_f32_32x32x16_bf16 v[66:81], v[138:141], v[2:5], v[66:81]
	ds_read_b128 v[2:5], v245 offset:20480
	ds_read_b128 v[182:185], v245 offset:21504
	ds_read_b128 v[186:189], v245 offset:22528
	ds_read_b128 v[190:193], v245 offset:23552
	s_waitcnt lgkmcnt(3)
	v_mfma_f32_32x32x16_bf16 v[18:33], v[134:137], v[2:5], 0
	v_mfma_f32_32x32x16_bf16 v[2:17], v[150:153], v[2:5], 0
	s_waitcnt lgkmcnt(2)
	v_mfma_f32_32x32x16_bf16 v[18:33], v[130:133], v[182:185], v[18:33]
	v_mfma_f32_32x32x16_bf16 v[2:17], v[146:149], v[182:185], v[2:17]
	v_lshlrev_b32_e32 v182, 1, v194
	s_waitcnt lgkmcnt(1)
	v_mfma_f32_32x32x16_bf16 v[18:33], v[126:129], v[186:189], v[18:33]
	v_mfma_f32_32x32x16_bf16 v[2:17], v[158:161], v[186:189], v[2:17]
	s_waitcnt lgkmcnt(0)
	v_mfma_f32_32x32x16_bf16 v[18:33], v[122:125], v[190:193], v[18:33]
	v_mfma_f32_32x32x16_bf16 v[2:17], v[154:157], v[190:193], v[2:17]
	s_cbranch_scc1 .LBB0_281
	v_mov_b32_e32 v183, v196
	v_lshl_add_u64 v[154:155], s[40:41], 0, v[182:183]
	s_add_i32 s68, s44, 0x800
	s_mov_b32 s69, s46
	s_mov_b32 s45, s46
	v_lshl_add_u64 v[146:147], s[68:69], 1, v[154:155]
	s_add_i32 s68, s44, 0xa00
	v_lshl_add_u64 v[122:123], s[44:45], 1, v[154:155]
	v_lshl_add_u64 v[148:149], s[68:69], 1, v[154:155]
	s_add_i32 s68, s44, 0xc00
	global_load_dwordx4 v[134:137], v[122:123], off
	global_load_dwordx4 v[130:133], v[122:123], off offset:1024
	global_load_dwordx4 v[126:129], v[122:123], off offset:2048
	s_nop 0
	global_load_dwordx4 v[122:125], v[122:123], off offset:3072
	v_lshl_add_u64 v[156:157], s[68:69], 1, v[154:155]
	s_add_i32 s68, s44, 0xe00
	v_lshl_add_u64 v[154:155], s[68:69], 1, v[154:155]
	global_load_dwordx4 v[150:153], v[146:147], off
	s_nop 0
	global_load_dwordx4 v[146:149], v[148:149], off
	s_nop 0
	global_load_dwordx4 v[158:161], v[156:157], off
	s_nop 0
	global_load_dwordx4 v[154:157], v[154:155], off

.LBB0_285:
	s_nop 5
	v_mov_b32_e32 v2, v183
	v_mov_b32_e32 v3, v183
	s_and_b64 vcc, exec, s[36:37]
	s_mov_b64 s[36:37], -1
	s_waitcnt lgkmcnt(0)
	v_permlane32_swap_b32_e32 v2, v3
	v_max_f32_e32 v2, v2, v3
	v_max3_f32 v231, v197, v183, v2
	v_sub_f32_e32 v2, v231, v197
	v_mov_b32_e32 v3, 0x41000000
	v_cmp_lt_f32_e64 s[82:83], v3, v2
	s_cmp_lg_u64 s[82:83], 0
	s_cselect_b32 s74, 1, 0
	s_cbranch_scc1 .Lat_need1
	v_mov_b32_e32 v231, v197
.Lat_need1:
	s_cbranch_vccnz .LBB0_287
	v_sub_f32_e32 v2, v190, v231
	v_exp_f32_e32 v2, v2
	v_sub_f32_e32 v3, v191, v231
	v_exp_f32_e32 v3, v3
	v_sub_f32_e32 v4, v188, v231
	v_exp_f32_e32 v4, v4
	v_add_f32_e32 v5, 0, v2
	v_add_f32_e32 v5, v3, v5
	v_sub_f32_e32 v6, v186, v231
	v_add_f32_e32 v9, v4, v5
	v_sub_f32_e32 v5, v189, v231
	v_exp_f32_e32 v5, v5
	v_exp_f32_e32 v6, v6
	v_sub_f32_e32 v7, v187, v231
	v_exp_f32_e32 v7, v7
	v_sub_f32_e32 v8, v184, v231
	v_exp_f32_e32 v8, v8
	v_add_f32_e32 v9, v5, v9
	v_add_f32_e32 v9, v6, v9
	v_add_f32_e32 v9, v7, v9
	v_add_f32_e32 v13, v8, v9
	v_sub_f32_e32 v9, v185, v231
	v_exp_f32_e32 v9, v9
	v_sub_f32_e32 v10, v204, v231
	v_exp_f32_e32 v10, v10
	v_sub_f32_e32 v11, v205, v231
	v_exp_f32_e32 v11, v11
	v_sub_f32_e32 v12, v202, v231
	v_exp_f32_e32 v12, v12
	v_add_f32_e32 v13, v9, v13
	v_add_f32_e32 v13, v10, v13
	v_add_f32_e32 v13, v11, v13
	v_add_f32_e32 v17, v12, v13
	v_sub_f32_e32 v13, v203, v231
	v_exp_f32_e32 v13, v13
	v_sub_f32_e32 v14, v194, v231
	v_exp_f32_e32 v14, v14
	v_sub_f32_e32 v15, v195, v231
	v_exp_f32_e32 v15, v15
	v_sub_f32_e32 v16, v192, v231
	v_exp_f32_e32 v16, v16
	v_add_f32_e32 v17, v13, v17
	v_add_f32_e32 v17, v14, v17
	v_add_f32_e32 v17, v15, v17
	v_add_f32_e32 v21, v16, v17
	v_sub_f32_e32 v17, v193, v231
	v_exp_f32_e32 v17, v17
	v_sub_f32_e32 v18, v220, v231
	v_exp_f32_e32 v18, v18
	v_sub_f32_e32 v19, v221, v231
	v_exp_f32_e32 v19, v19
	v_sub_f32_e32 v20, v218, v231
	v_exp_f32_e32 v20, v20
	v_add_f32_e32 v21, v17, v21
	v_add_f32_e32 v21, v18, v21
	v_add_f32_e32 v21, v19, v21
	v_add_f32_e32 v25, v20, v21
	v_sub_f32_e32 v21, v219, v231
	v_exp_f32_e32 v21, v21
	v_sub_f32_e32 v22, v216, v231
	v_exp_f32_e32 v22, v22
	v_sub_f32_e32 v23, v217, v231
	v_exp_f32_e32 v23, v23
	v_sub_f32_e32 v24, v214, v231
	v_exp_f32_e32 v24, v24
	v_add_f32_e32 v25, v21, v25
	v_add_f32_e32 v25, v22, v25
	v_add_f32_e32 v25, v23, v25
	v_add_f32_e32 v29, v24, v25
	v_sub_f32_e32 v25, v215, v231
	v_exp_f32_e32 v25, v25
	v_sub_f32_e32 v26, v212, v231
	v_exp_f32_e32 v26, v26
	v_sub_f32_e32 v27, v213, v231
	v_exp_f32_e32 v27, v27
	v_sub_f32_e32 v28, v210, v231
	v_exp_f32_e32 v28, v28
	v_add_f32_e32 v29, v25, v29
	v_add_f32_e32 v29, v26, v29
	v_add_f32_e32 v29, v27, v29
	v_add_f32_e32 v33, v28, v29
	v_sub_f32_e32 v29, v211, v231
	v_exp_f32_e32 v29, v29
	v_sub_f32_e32 v30, v208, v231
	v_exp_f32_e32 v30, v30
	v_sub_f32_e32 v31, v209, v231
	v_exp_f32_e32 v31, v31
	v_sub_f32_e32 v32, v206, v231
	v_exp_f32_e32 v32, v32
	v_add_f32_e32 v33, v29, v33
	v_add_f32_e32 v33, v30, v33
	v_add_f32_e32 v33, v31, v33
	v_add_f32_e32 v222, v32, v33
	v_sub_f32_e32 v223, v207, v231
	s_mov_b64 s[36:37], 0

.LBB0_289:
	v_sub_f32_e32 v33, v197, v231
	v_exp_f32_e32 v184, v33
	v_cvt_pk_bf16_f32 v2, v2, v3
	v_cvt_pk_bf16_f32 v3, v4, v5
	v_cvt_pk_bf16_f32 v4, v6, v7
	v_cvt_pk_bf16_f32 v5, v8, v9
	v_cvt_pk_bf16_f32 v6, v30, v31
	s_nop 0
	s_cmp_eq_u32 s74, 0
	s_cbranch_scc1 .Lat_skip1
	v_pk_mul_f32 v[64:65], v[64:65], v[184:185] op_sel_hi:[1,0]
	v_pk_mul_f32 v[62:63], v[62:63], v[184:185] op_sel_hi:[1,0]
	v_pk_mul_f32 v[60:61], v[60:61], v[184:185] op_sel_hi:[1,0]
	v_pk_mul_f32 v[58:59], v[58:59], v[184:185] op_sel_hi:[1,0]
	v_pk_mul_f32 v[56:57], v[56:57], v[184:185] op_sel_hi:[1,0]
	v_pk_mul_f32 v[54:55], v[54:55], v[184:185] op_sel_hi:[1,0]
	v_pk_mul_f32 v[52:53], v[52:53], v[184:185] op_sel_hi:[1,0]
	v_pk_mul_f32 v[50:51], v[50:51], v[184:185] op_sel_hi:[1,0]
	v_pk_mul_f32 v[48:49], v[48:49], v[184:185] op_sel_hi:[1,0]
	v_pk_mul_f32 v[46:47], v[46:47], v[184:185] op_sel_hi:[1,0]
	v_pk_mul_f32 v[44:45], v[44:45], v[184:185] op_sel_hi:[1,0]
	v_pk_mul_f32 v[42:43], v[42:43], v[184:185] op_sel_hi:[1,0]
	v_pk_mul_f32 v[40:41], v[40:41], v[184:185] op_sel_hi:[1,0]
	v_pk_mul_f32 v[38:39], v[38:39], v[184:185] op_sel_hi:[1,0]
	v_pk_mul_f32 v[36:37], v[36:37], v[184:185] op_sel_hi:[1,0]
	v_pk_mul_f32 v[34:35], v[34:35], v[184:185] op_sel_hi:[1,0]
.Lat_skip1:
	v_mfma_f32_32x32x16_bf16 v[50:65], v[118:121], v[2:5], v[50:65]
	s_andn2_b64 vcc, exec, s[16:17]
	v_mfma_f32_32x32x16_bf16 v[34:49], v[110:113], v[2:5], v[34:49]
	v_cvt_pk_bf16_f32 v2, v10, v11
	v_cvt_pk_bf16_f32 v3, v12, v13
	v_cvt_pk_bf16_f32 v4, v14, v15
	v_cvt_pk_bf16_f32 v5, v16, v17
	s_nop 0
	v_mfma_f32_32x32x16_bf16 v[50:65], v[114:117], v[2:5], v[50:65]
	v_mfma_f32_32x32x16_bf16 v[34:49], v[106:109], v[2:5], v[34:49]
	v_cvt_pk_bf16_f32 v2, v18, v19
	v_cvt_pk_bf16_f32 v3, v20, v21
	v_cvt_pk_bf16_f32 v4, v22, v23
	v_cvt_pk_bf16_f32 v5, v24, v25
	s_nop 0
	v_mfma_f32_32x32x16_bf16 v[50:65], v[102:105], v[2:5], v[50:65]
	v_mfma_f32_32x32x16_bf16 v[34:49], v[142:145], v[2:5], v[34:49]
	v_exp_f32_e32 v2, v223
	v_cvt_pk_bf16_f32 v4, v26, v27
	v_cvt_pk_bf16_f32 v5, v28, v29
	v_cvt_pk_bf16_f32 v7, v32, v2
	s_nop 0
	v_mfma_f32_32x32x16_bf16 v[50:65], v[98:101], v[4:7], v[50:65]
	v_mfma_f32_32x32x16_bf16 v[34:49], v[138:141], v[4:7], v[34:49]
	s_cbranch_vccnz .LBB0_291
	v_mov_b32_e32 v183, v196
	v_lshl_add_u64 v[4:5], s[42:43], 0, v[182:183]
	s_add_i32 s16, s44, 0x800
	s_mov_b32 s17, s46
	s_mov_b32 s45, s46
	v_lshl_add_u64 v[8:9], s[16:17], 1, v[4:5]
	s_add_i32 s16, s44, 0xc00
	v_lshl_add_u64 v[6:7], s[44:45], 1, v[4:5]
	v_lshl_add_u64 v[10:11], s[16:17], 1, v[4:5]
	global_load_dwordx4 v[102:105], v[8:9], off
	global_load_dwordx4 v[98:101], v[10:11], off
	global_load_dwordx4 v[118:121], v[6:7], off
	global_load_dwordx4 v[110:113], v[6:7], off offset:1024
	global_load_dwordx4 v[114:117], v[6:7], off offset:2048
	global_load_dwordx4 v[106:109], v[6:7], off offset:3072
	s_add_i32 s16, s44, 0xa00
	v_lshl_add_u64 v[6:7], s[16:17], 1, v[4:5]
	s_add_i32 s16, s44, 0xe00
	v_lshl_add_u64 v[4:5], s[16:17], 1, v[4:5]
	global_load_dwordx4 v[142:145], v[6:7], off
	global_load_dwordx4 v[138:141], v[4:5], off
